# baseline (speedup 1.0000x reference)
.LBB0_395:
.Lfz1_c0:
	s_and_b32 s27, s86, 0xc000
	v_add_u32_e32 v241, s27, v233
	ds_read_b128 v[144:147], v241 offset:0
	v_xor_b32_e32 v240, 32, v241
	ds_read_b128 v[148:151], v240 offset:0
	v_xor_b32_e32 v239, 64, v241
	ds_read_b128 v[152:155], v239 offset:0
	v_xor_b32_e32 v0, 0x60, v241
	ds_read_b128 v[156:159], v0 offset:0
	s_waitcnt lgkmcnt(0)
	v_mfma_f32_32x32x16_bf16 v[212:227], v[144:147], v[176:179], 0
	v_mfma_f32_32x32x16_bf16 v[212:227], v[148:151], v[180:183], v[212:227]
	v_mfma_f32_32x32x16_bf16 v[212:227], v[152:155], v[184:187], v[212:227]
	v_mfma_f32_32x32x16_bf16 v[212:227], v[156:159], v[188:191], v[212:227]
	ds_read_b128 v[144:147], v241 offset:0x80
	ds_read_b128 v[148:151], v240 offset:0x80
	ds_read_b128 v[152:155], v239 offset:0x80
	ds_read_b128 v[156:159], v0 offset:0x80
	v_cmp_eq_f32_e32 vcc, 0, v238
	v_cmp_eq_f32_e64 s[10:11], 0, v237
	s_and_b64 s[0:1], vcc, s[10:11]
	s_cmp_eq_u64 s[0:1], exec
	s_waitcnt lgkmcnt(0)
	v_mfma_f32_32x32x16_bf16 v[160:175], v[144:147], v[192:195], 0
	v_mfma_f32_32x32x16_bf16 v[160:175], v[148:151], v[196:199], v[160:175]
	v_mfma_f32_32x32x16_bf16 v[160:175], v[152:155], v[200:203], v[160:175]
	v_mfma_f32_32x32x16_bf16 v[160:175], v[156:159], v[204:207], v[160:175]
	s_cbranch_scc0 .LBB0_397
	v_exp_f32_e32 v144, v212
	v_exp_f32_e32 v145, v213
	v_exp_f32_e32 v146, v214
	v_exp_f32_e32 v147, v215
	v_exp_f32_e32 v148, v216
	v_exp_f32_e32 v149, v217
	v_exp_f32_e32 v150, v218
	v_exp_f32_e32 v151, v219
	v_exp_f32_e32 v152, v220
	v_exp_f32_e32 v153, v221
	v_exp_f32_e32 v154, v222
	v_exp_f32_e32 v155, v223
	v_exp_f32_e32 v156, v224
	v_exp_f32_e32 v157, v225
	v_exp_f32_e32 v158, v226
	v_exp_f32_e32 v159, v227
	v_add_f32_e32 v252, v144, v145
	v_add_f32_e32 v253, v146, v147
	v_add_f32_e32 v254, v148, v149
	v_add_f32_e32 v255, v150, v151
	v_add_f32_e32 v252, v252, v152
	v_add_f32_e32 v253, v253, v153
	v_add_f32_e32 v254, v254, v154
	v_add_f32_e32 v255, v255, v155
	v_add_f32_e32 v252, v252, v156
	v_add_f32_e32 v253, v253, v157
	v_add_f32_e32 v254, v254, v158
	v_add_f32_e32 v255, v255, v159
	v_cvt_pk_bf16_f32 v216, v144, v145
	v_cvt_pk_bf16_f32 v217, v146, v147
	v_add_f32_e32 v252, v252, v253
	v_add_f32_e32 v254, v254, v255
	v_cvt_pk_bf16_f32 v218, v148, v149
	v_cvt_pk_bf16_f32 v219, v150, v151
	v_cvt_pk_bf16_f32 v224, v152, v153
	v_add_f32_e32 v252, v252, v254
	v_cvt_pk_bf16_f32 v225, v154, v155
	v_cvt_pk_bf16_f32 v226, v156, v157
	v_cvt_pk_bf16_f32 v227, v158, v159
	v_add_u32_e32 v253, 0xde801b54, v252
	v_cmp_gt_u32_e32 vcc, 0x3bff7543, v253
	s_cmp_lg_u64 vcc, exec
	s_cbranch_scc1 .LBB0_432
	v_add_f32_e32 v15, v15, v252
	v_exp_f32_e32 v144, v160
	v_exp_f32_e32 v145, v161
	v_exp_f32_e32 v146, v162
	v_exp_f32_e32 v147, v163
	v_exp_f32_e32 v148, v164
	v_exp_f32_e32 v149, v165
	v_exp_f32_e32 v150, v166
	v_exp_f32_e32 v151, v167
	v_exp_f32_e32 v152, v168
	v_exp_f32_e32 v153, v169
	v_exp_f32_e32 v154, v170
	v_exp_f32_e32 v155, v171
	v_exp_f32_e32 v156, v172
	v_exp_f32_e32 v157, v173
	v_exp_f32_e32 v158, v174
	v_exp_f32_e32 v159, v175
	v_add_f32_e32 v252, v144, v145
	v_add_f32_e32 v253, v146, v147
	v_add_f32_e32 v254, v148, v149
	v_add_f32_e32 v255, v150, v151
	v_add_f32_e32 v252, v252, v152
	v_add_f32_e32 v253, v253, v153
	v_add_f32_e32 v254, v254, v154
	v_add_f32_e32 v255, v255, v155
	v_add_f32_e32 v252, v252, v156
	v_add_f32_e32 v253, v253, v157
	v_add_f32_e32 v254, v254, v158
	v_add_f32_e32 v255, v255, v159
	v_cvt_pk_bf16_f32 v212, v144, v145
	v_cvt_pk_bf16_f32 v213, v146, v147
	v_add_f32_e32 v252, v252, v253
	v_add_f32_e32 v254, v254, v255
	v_cvt_pk_bf16_f32 v214, v148, v149
	v_cvt_pk_bf16_f32 v215, v150, v151
	v_cvt_pk_bf16_f32 v220, v152, v153
	v_add_f32_e32 v252, v252, v254
	v_cvt_pk_bf16_f32 v221, v154, v155
	v_cvt_pk_bf16_f32 v222, v156, v157
	v_cvt_pk_bf16_f32 v223, v158, v159
	v_add_u32_e32 v253, 0xde801b54, v252
	v_cmp_gt_u32_e32 vcc, 0x3bff7543, v253
	s_cmp_lg_u64 vcc, exec
	s_cbranch_scc1 .Lfzsb1_c0
	v_add_f32_e32 v14, v14, v252
	s_branch .LBB0_413

.LBB0_429:
	ds_read_b64_tr_b16 v[160:161], v242 offset:0x2000
	ds_read_b64_tr_b16 v[162:163], v242 offset:0x2100
	ds_read_b64_tr_b16 v[164:165], v242 offset:0x3000
	ds_read_b64_tr_b16 v[166:167], v242 offset:0x3100
	s_waitcnt lgkmcnt(2)
	v_mfma_f32_32x32x16_bf16 v[128:143], v[6:9], v[160:163], v[128:143]
	ds_read_b64_tr_b16 v[168:169], v242 offset:0x2200
	v_mfma_f32_32x32x16_bf16 v[96:111], v[2:5], v[160:163], v[96:111]
	ds_read_b64_tr_b16 v[170:171], v242 offset:0x2300
	s_waitcnt lgkmcnt(2)
	v_mfma_f32_32x32x16_bf16 v[128:143], v[208:211], v[164:167], v[128:143]
	ds_read_b64_tr_b16 v[172:173], v242 offset:0x3200
	v_mfma_f32_32x32x16_bf16 v[96:111], v[10:13], v[164:167], v[96:111]
	ds_read_b64_tr_b16 v[174:175], v242 offset:0x3300
	s_waitcnt lgkmcnt(2)
	v_mfma_f32_32x32x16_bf16 v[112:127], v[6:9], v[168:171], v[112:127]
	ds_read_b64_tr_b16 v[160:161], v242 offset:0x2400
	v_mfma_f32_32x32x16_bf16 v[80:95], v[2:5], v[168:171], v[80:95]
	ds_read_b64_tr_b16 v[162:163], v242 offset:0x2500
	s_waitcnt lgkmcnt(2)
	v_mfma_f32_32x32x16_bf16 v[112:127], v[208:211], v[172:175], v[112:127]
	ds_read_b64_tr_b16 v[164:165], v242 offset:0x3400
	v_mfma_f32_32x32x16_bf16 v[80:95], v[10:13], v[172:175], v[80:95]
	ds_read_b64_tr_b16 v[166:167], v242 offset:0x3500
	s_waitcnt lgkmcnt(2)
	v_mfma_f32_32x32x16_bf16 v[64:79], v[6:9], v[160:163], v[64:79]
	ds_read_b64_tr_b16 v[168:169], v242 offset:0x2600
	v_mfma_f32_32x32x16_bf16 v[32:47], v[2:5], v[160:163], v[32:47]
	ds_read_b64_tr_b16 v[170:171], v242 offset:0x2700
	s_waitcnt lgkmcnt(2)
	v_mfma_f32_32x32x16_bf16 v[64:79], v[208:211], v[164:167], v[64:79]
	ds_read_b64_tr_b16 v[172:173], v242 offset:0x3600
	v_mfma_f32_32x32x16_bf16 v[32:47], v[10:13], v[164:167], v[32:47]
	ds_read_b64_tr_b16 v[174:175], v242 offset:0x3700
	s_waitcnt lgkmcnt(2)
	v_mfma_f32_32x32x16_bf16 v[48:63], v[6:9], v[168:171], v[48:63]
	v_mfma_f32_32x32x16_bf16 v[16:31], v[2:5], v[168:171], v[16:31]
	s_waitcnt lgkmcnt(0)
	v_mfma_f32_32x32x16_bf16 v[48:63], v[208:211], v[172:175], v[48:63]
	v_mfma_f32_32x32x16_bf16 v[16:31], v[10:13], v[172:175], v[16:31]
	s_branch .LBB0_388

.LBB0_463:
.LBB0_465:
	v_mov_b32_e32 v252, v15
	v_mov_b32_e32 v253, v14
	s_nop 1
	v_permlane32_swap_b32_e32 v15, v252
	v_permlane32_swap_b32_e32 v14, v253
	v_add_f32_e32 v15, v15, v252
	v_add_f32_e32 v14, v14, v253
	v_mov_b32_e32 v2, v228
	v_readlane_b32 s50, v249, 48
	v_bfe_u32 v5, v2, 5, 1
	v_and_b32_e32 v3, 0x3fffffc0, v2
	v_readlane_b32 s44, v249, 57
	v_readlane_b32 s45, v249, 58
	v_and_b32_e32 v0, 31, v2
	v_lshl_add_u32 v3, v3, 2, s31
	v_cmp_eq_u32_e32 vcc, 0, v5
	v_readlane_b32 s51, v249, 49
	s_and_saveexec_b64 s[0:1], vcc
	s_cbranch_execz .LBB0_386
	v_div_scale_f32 v4, s[8:9], v15, v15, 1.0
	v_rcp_f32_e32 v6, v4
	v_div_scale_f32 v7, vcc, 1.0, v15, 1.0
	v_fma_f32 v8, -v4, v6, 1.0
	v_fmac_f32_e32 v6, v8, v6
	v_mul_f32_e32 v8, v7, v6
	v_fma_f32 v9, -v4, v8, v7
	v_fmac_f32_e32 v8, v9, v6
	v_fma_f32 v4, -v4, v8, v7
	v_div_scale_f32 v7, s[8:9], v14, v14, v229
	v_rcp_f32_e32 v9, v7
	v_div_fmas_f32 v4, v4, v6, v8
	v_div_fixup_f32 v4, v4, v15, 1.0
	v_lshl_add_u32 v6, v0, 2, v3
	v_fma_f32 v8, -v7, v9, 1.0
	v_fmac_f32_e32 v9, v8, v9
	v_div_scale_f32 v8, vcc, v229, v14, v229
	v_mul_f32_e32 v10, v8, v9
	v_fma_f32 v11, -v7, v10, v8
	v_fmac_f32_e32 v10, v11, v9
	v_fma_f32 v7, -v7, v10, v8
	v_div_fmas_f32 v7, v7, v9, v10
	v_div_fixup_f32 v7, v7, v14, v229
	ds_write2_b32 v6, v4, v7 offset1:32
	s_branch .LBB0_386

.LBB0_1249:
.Lfz1_c1:
	s_and_b32 s27, s77, 0xc000
	v_add_u32_e32 v241, s27, v233
	ds_read_b128 v[144:147], v241 offset:0
	v_xor_b32_e32 v240, 32, v241
	ds_read_b128 v[148:151], v240 offset:0
	v_xor_b32_e32 v239, 64, v241
	ds_read_b128 v[152:155], v239 offset:0
	v_xor_b32_e32 v0, 0x60, v241
	ds_read_b128 v[156:159], v0 offset:0
	s_waitcnt lgkmcnt(0)
	v_mfma_f32_32x32x16_bf16 v[212:227], v[144:147], v[176:179], 0
	v_mfma_f32_32x32x16_bf16 v[212:227], v[148:151], v[180:183], v[212:227]
	v_mfma_f32_32x32x16_bf16 v[212:227], v[152:155], v[184:187], v[212:227]
	v_mfma_f32_32x32x16_bf16 v[212:227], v[156:159], v[188:191], v[212:227]
	ds_read_b128 v[144:147], v241 offset:0x80
	ds_read_b128 v[148:151], v240 offset:0x80
	ds_read_b128 v[152:155], v239 offset:0x80
	ds_read_b128 v[156:159], v0 offset:0x80
	v_cmp_eq_f32_e32 vcc, 0, v238
	v_cmp_eq_f32_e64 s[10:11], 0, v237
	s_and_b64 s[0:1], vcc, s[10:11]
	s_cmp_eq_u64 s[0:1], exec
	s_waitcnt lgkmcnt(0)
	v_mfma_f32_32x32x16_bf16 v[160:175], v[144:147], v[192:195], 0
	v_mfma_f32_32x32x16_bf16 v[160:175], v[148:151], v[196:199], v[160:175]
	v_mfma_f32_32x32x16_bf16 v[160:175], v[152:155], v[200:203], v[160:175]
	v_mfma_f32_32x32x16_bf16 v[160:175], v[156:159], v[204:207], v[160:175]
	s_cbranch_scc0 .LBB0_1251
	v_exp_f32_e32 v144, v212
	v_exp_f32_e32 v145, v213
	v_exp_f32_e32 v146, v214
	v_exp_f32_e32 v147, v215
	v_exp_f32_e32 v148, v216
	v_exp_f32_e32 v149, v217
	v_exp_f32_e32 v150, v218
	v_exp_f32_e32 v151, v219
	v_exp_f32_e32 v152, v220
	v_exp_f32_e32 v153, v221
	v_exp_f32_e32 v154, v222
	v_exp_f32_e32 v155, v223
	v_exp_f32_e32 v156, v224
	v_exp_f32_e32 v157, v225
	v_exp_f32_e32 v158, v226
	v_exp_f32_e32 v159, v227
	v_add_f32_e32 v252, v144, v145
	v_add_f32_e32 v253, v146, v147
	v_add_f32_e32 v254, v148, v149
	v_add_f32_e32 v255, v150, v151
	v_add_f32_e32 v252, v252, v152
	v_add_f32_e32 v253, v253, v153
	v_add_f32_e32 v254, v254, v154
	v_add_f32_e32 v255, v255, v155
	v_add_f32_e32 v252, v252, v156
	v_add_f32_e32 v253, v253, v157
	v_add_f32_e32 v254, v254, v158
	v_add_f32_e32 v255, v255, v159
	v_cvt_pk_bf16_f32 v216, v144, v145
	v_cvt_pk_bf16_f32 v217, v146, v147
	v_add_f32_e32 v252, v252, v253
	v_add_f32_e32 v254, v254, v255
	v_cvt_pk_bf16_f32 v218, v148, v149
	v_cvt_pk_bf16_f32 v219, v150, v151
	v_cvt_pk_bf16_f32 v224, v152, v153
	v_add_f32_e32 v252, v252, v254
	v_cvt_pk_bf16_f32 v225, v154, v155
	v_cvt_pk_bf16_f32 v226, v156, v157
	v_cvt_pk_bf16_f32 v227, v158, v159
	v_add_u32_e32 v253, 0xde801b54, v252
	v_cmp_gt_u32_e32 vcc, 0x3bff7543, v253
	s_cmp_lg_u64 vcc, exec
	s_cbranch_scc1 .LBB0_1286
	v_add_f32_e32 v15, v15, v252
	v_exp_f32_e32 v144, v160
	v_exp_f32_e32 v145, v161
	v_exp_f32_e32 v146, v162
	v_exp_f32_e32 v147, v163
	v_exp_f32_e32 v148, v164
	v_exp_f32_e32 v149, v165
	v_exp_f32_e32 v150, v166
	v_exp_f32_e32 v151, v167
	v_exp_f32_e32 v152, v168
	v_exp_f32_e32 v153, v169
	v_exp_f32_e32 v154, v170
	v_exp_f32_e32 v155, v171
	v_exp_f32_e32 v156, v172
	v_exp_f32_e32 v157, v173
	v_exp_f32_e32 v158, v174
	v_exp_f32_e32 v159, v175
	v_add_f32_e32 v252, v144, v145
	v_add_f32_e32 v253, v146, v147
	v_add_f32_e32 v254, v148, v149
	v_add_f32_e32 v255, v150, v151
	v_add_f32_e32 v252, v252, v152
	v_add_f32_e32 v253, v253, v153
	v_add_f32_e32 v254, v254, v154
	v_add_f32_e32 v255, v255, v155
	v_add_f32_e32 v252, v252, v156
	v_add_f32_e32 v253, v253, v157
	v_add_f32_e32 v254, v254, v158
	v_add_f32_e32 v255, v255, v159
	v_cvt_pk_bf16_f32 v212, v144, v145
	v_cvt_pk_bf16_f32 v213, v146, v147
	v_add_f32_e32 v252, v252, v253
	v_add_f32_e32 v254, v254, v255
	v_cvt_pk_bf16_f32 v214, v148, v149
	v_cvt_pk_bf16_f32 v215, v150, v151
	v_cvt_pk_bf16_f32 v220, v152, v153
	v_add_f32_e32 v252, v252, v254
	v_cvt_pk_bf16_f32 v221, v154, v155
	v_cvt_pk_bf16_f32 v222, v156, v157
	v_cvt_pk_bf16_f32 v223, v158, v159
	v_add_u32_e32 v253, 0xde801b54, v252
	v_cmp_gt_u32_e32 vcc, 0x3bff7543, v253
	s_cmp_lg_u64 vcc, exec
	s_cbranch_scc1 .Lfzsb1_c1
	v_add_f32_e32 v14, v14, v252
	s_branch .LBB0_1267

.LBB0_1283:
	ds_read_b64_tr_b16 v[160:161], v242 offset:0x2000
	ds_read_b64_tr_b16 v[162:163], v242 offset:0x2100
	ds_read_b64_tr_b16 v[164:165], v242 offset:0x3000
	ds_read_b64_tr_b16 v[166:167], v242 offset:0x3100
	s_waitcnt lgkmcnt(2)
	v_mfma_f32_32x32x16_bf16 v[128:143], v[6:9], v[160:163], v[128:143]
	ds_read_b64_tr_b16 v[168:169], v242 offset:0x2200
	v_mfma_f32_32x32x16_bf16 v[96:111], v[2:5], v[160:163], v[96:111]
	ds_read_b64_tr_b16 v[170:171], v242 offset:0x2300
	s_waitcnt lgkmcnt(2)
	v_mfma_f32_32x32x16_bf16 v[128:143], v[208:211], v[164:167], v[128:143]
	ds_read_b64_tr_b16 v[172:173], v242 offset:0x3200
	v_mfma_f32_32x32x16_bf16 v[96:111], v[10:13], v[164:167], v[96:111]
	ds_read_b64_tr_b16 v[174:175], v242 offset:0x3300
	s_waitcnt lgkmcnt(2)
	v_mfma_f32_32x32x16_bf16 v[112:127], v[6:9], v[168:171], v[112:127]
	ds_read_b64_tr_b16 v[160:161], v242 offset:0x2400
	v_mfma_f32_32x32x16_bf16 v[80:95], v[2:5], v[168:171], v[80:95]
	ds_read_b64_tr_b16 v[162:163], v242 offset:0x2500
	s_waitcnt lgkmcnt(2)
	v_mfma_f32_32x32x16_bf16 v[112:127], v[208:211], v[172:175], v[112:127]
	ds_read_b64_tr_b16 v[164:165], v242 offset:0x3400
	v_mfma_f32_32x32x16_bf16 v[80:95], v[10:13], v[172:175], v[80:95]
	ds_read_b64_tr_b16 v[166:167], v242 offset:0x3500
	s_waitcnt lgkmcnt(2)
	v_mfma_f32_32x32x16_bf16 v[64:79], v[6:9], v[160:163], v[64:79]
	ds_read_b64_tr_b16 v[168:169], v242 offset:0x2600
	v_mfma_f32_32x32x16_bf16 v[48:63], v[2:5], v[160:163], v[48:63]
	ds_read_b64_tr_b16 v[170:171], v242 offset:0x2700
	s_waitcnt lgkmcnt(2)
	v_mfma_f32_32x32x16_bf16 v[64:79], v[208:211], v[164:167], v[64:79]
	ds_read_b64_tr_b16 v[172:173], v242 offset:0x3600
	v_mfma_f32_32x32x16_bf16 v[48:63], v[10:13], v[164:167], v[48:63]
	ds_read_b64_tr_b16 v[174:175], v242 offset:0x3700
	s_waitcnt lgkmcnt(2)
	v_mfma_f32_32x32x16_bf16 v[32:47], v[6:9], v[168:171], v[32:47]
	v_mfma_f32_32x32x16_bf16 v[16:31], v[2:5], v[168:171], v[16:31]
	s_waitcnt lgkmcnt(0)
	v_mfma_f32_32x32x16_bf16 v[32:47], v[208:211], v[172:175], v[32:47]
	v_mfma_f32_32x32x16_bf16 v[16:31], v[10:13], v[172:175], v[16:31]
	s_branch .LBB0_1242

.LBB0_1317:
.LBB0_1319:
	v_mov_b32_e32 v252, v15
	v_mov_b32_e32 v253, v14
	s_nop 1
	v_permlane32_swap_b32_e32 v15, v252
	v_permlane32_swap_b32_e32 v14, v253
	v_add_f32_e32 v15, v15, v252
	v_add_f32_e32 v14, v14, v253
	v_mov_b32_e32 v2, v228
	v_readlane_b32 s50, v249, 48
	v_bfe_u32 v9, v2, 5, 1
	v_and_b32_e32 v3, 0x3fffffc0, v2
	v_readlane_b32 s3, v249, 57
	v_readlane_b32 s10, v249, 58
	v_and_b32_e32 v0, 31, v2
	v_lshl_add_u32 v8, v3, 2, s25
	v_cmp_eq_u32_e32 vcc, 0, v9
	v_readlane_b32 s51, v249, 49
	s_and_saveexec_b64 s[8:9], vcc
	s_cbranch_execz .LBB0_1240
	v_div_scale_f32 v3, s[0:1], v15, v15, 1.0
	v_rcp_f32_e32 v4, v3
	s_nop 0
	v_fma_f32 v5, -v3, v4, 1.0
	v_fmac_f32_e32 v4, v5, v4
	v_div_scale_f32 v5, vcc, 1.0, v15, 1.0
	v_mul_f32_e32 v6, v5, v4
	v_fma_f32 v7, -v3, v6, v5
	v_fmac_f32_e32 v6, v7, v4
	v_fma_f32 v3, -v3, v6, v5
	v_div_scale_f32 v5, s[0:1], v14, v14, v229
	v_div_fmas_f32 v3, v3, v4, v6
	v_rcp_f32_e32 v6, v5
	v_div_fixup_f32 v3, v3, v15, 1.0
	v_lshl_add_u32 v4, v0, 2, v8
	v_fma_f32 v7, -v5, v6, 1.0
	v_fmac_f32_e32 v6, v7, v6
	v_div_scale_f32 v7, vcc, v229, v14, v229
	v_mul_f32_e32 v10, v7, v6
	v_fma_f32 v11, -v5, v10, v7
	v_fmac_f32_e32 v10, v11, v6
	v_fma_f32 v5, -v5, v10, v7
	v_div_fmas_f32 v5, v5, v6, v10
	v_div_fixup_f32 v5, v5, v14, v229
	ds_write2_b32 v4, v3, v5 offset1:32
	s_branch .LBB0_1240

.LBB0_2103:
.Lfz1_c2:
	s_and_b32 s27, s68, 0xc000
	v_add_u32_e32 v241, s27, v233
	ds_read_b128 v[144:147], v241 offset:0
	v_xor_b32_e32 v240, 32, v241
	ds_read_b128 v[148:151], v240 offset:0
	v_xor_b32_e32 v239, 64, v241
	ds_read_b128 v[152:155], v239 offset:0
	v_xor_b32_e32 v0, 0x60, v241
	ds_read_b128 v[156:159], v0 offset:0
	s_waitcnt lgkmcnt(0)
	v_mfma_f32_32x32x16_bf16 v[212:227], v[144:147], v[176:179], 0
	v_mfma_f32_32x32x16_bf16 v[212:227], v[148:151], v[180:183], v[212:227]
	v_mfma_f32_32x32x16_bf16 v[212:227], v[152:155], v[184:187], v[212:227]
	v_mfma_f32_32x32x16_bf16 v[212:227], v[156:159], v[188:191], v[212:227]
	ds_read_b128 v[144:147], v241 offset:0x80
	ds_read_b128 v[148:151], v240 offset:0x80
	ds_read_b128 v[152:155], v239 offset:0x80
	ds_read_b128 v[156:159], v0 offset:0x80
	v_cmp_eq_f32_e32 vcc, 0, v238
	v_cmp_eq_f32_e64 s[6:7], 0, v237
	s_and_b64 s[0:1], vcc, s[6:7]
	s_cmp_eq_u64 s[0:1], exec
	s_waitcnt lgkmcnt(0)
	v_mfma_f32_32x32x16_bf16 v[160:175], v[144:147], v[192:195], 0
	v_mfma_f32_32x32x16_bf16 v[160:175], v[148:151], v[196:199], v[160:175]
	v_mfma_f32_32x32x16_bf16 v[160:175], v[152:155], v[200:203], v[160:175]
	v_mfma_f32_32x32x16_bf16 v[160:175], v[156:159], v[204:207], v[160:175]
	s_cbranch_scc0 .LBB0_2105
	v_exp_f32_e32 v144, v212
	v_exp_f32_e32 v145, v213
	v_exp_f32_e32 v146, v214
	v_exp_f32_e32 v147, v215
	v_exp_f32_e32 v148, v216
	v_exp_f32_e32 v149, v217
	v_exp_f32_e32 v150, v218
	v_exp_f32_e32 v151, v219
	v_exp_f32_e32 v152, v220
	v_exp_f32_e32 v153, v221
	v_exp_f32_e32 v154, v222
	v_exp_f32_e32 v155, v223
	v_exp_f32_e32 v156, v224
	v_exp_f32_e32 v157, v225
	v_exp_f32_e32 v158, v226
	v_exp_f32_e32 v159, v227
	v_add_f32_e32 v252, v144, v145
	v_add_f32_e32 v253, v146, v147
	v_add_f32_e32 v254, v148, v149
	v_add_f32_e32 v255, v150, v151
	v_add_f32_e32 v252, v252, v152
	v_add_f32_e32 v253, v253, v153
	v_add_f32_e32 v254, v254, v154
	v_add_f32_e32 v255, v255, v155
	v_add_f32_e32 v252, v252, v156
	v_add_f32_e32 v253, v253, v157
	v_add_f32_e32 v254, v254, v158
	v_add_f32_e32 v255, v255, v159
	v_cvt_pk_bf16_f32 v216, v144, v145
	v_cvt_pk_bf16_f32 v217, v146, v147
	v_add_f32_e32 v252, v252, v253
	v_add_f32_e32 v254, v254, v255
	v_cvt_pk_bf16_f32 v218, v148, v149
	v_cvt_pk_bf16_f32 v219, v150, v151
	v_cvt_pk_bf16_f32 v224, v152, v153
	v_add_f32_e32 v252, v252, v254
	v_cvt_pk_bf16_f32 v225, v154, v155
	v_cvt_pk_bf16_f32 v226, v156, v157
	v_cvt_pk_bf16_f32 v227, v158, v159
	v_add_u32_e32 v253, 0xde801b54, v252
	v_cmp_gt_u32_e32 vcc, 0x3bff7543, v253
	s_cmp_lg_u64 vcc, exec
	s_cbranch_scc1 .LBB0_2140
	v_add_f32_e32 v15, v15, v252
	v_exp_f32_e32 v144, v160
	v_exp_f32_e32 v145, v161
	v_exp_f32_e32 v146, v162
	v_exp_f32_e32 v147, v163
	v_exp_f32_e32 v148, v164
	v_exp_f32_e32 v149, v165
	v_exp_f32_e32 v150, v166
	v_exp_f32_e32 v151, v167
	v_exp_f32_e32 v152, v168
	v_exp_f32_e32 v153, v169
	v_exp_f32_e32 v154, v170
	v_exp_f32_e32 v155, v171
	v_exp_f32_e32 v156, v172
	v_exp_f32_e32 v157, v173
	v_exp_f32_e32 v158, v174
	v_exp_f32_e32 v159, v175
	v_add_f32_e32 v252, v144, v145
	v_add_f32_e32 v253, v146, v147
	v_add_f32_e32 v254, v148, v149
	v_add_f32_e32 v255, v150, v151
	v_add_f32_e32 v252, v252, v152
	v_add_f32_e32 v253, v253, v153
	v_add_f32_e32 v254, v254, v154
	v_add_f32_e32 v255, v255, v155
	v_add_f32_e32 v252, v252, v156
	v_add_f32_e32 v253, v253, v157
	v_add_f32_e32 v254, v254, v158
	v_add_f32_e32 v255, v255, v159
	v_cvt_pk_bf16_f32 v212, v144, v145
	v_cvt_pk_bf16_f32 v213, v146, v147
	v_add_f32_e32 v252, v252, v253
	v_add_f32_e32 v254, v254, v255
	v_cvt_pk_bf16_f32 v214, v148, v149
	v_cvt_pk_bf16_f32 v215, v150, v151
	v_cvt_pk_bf16_f32 v220, v152, v153
	v_add_f32_e32 v252, v252, v254
	v_cvt_pk_bf16_f32 v221, v154, v155
	v_cvt_pk_bf16_f32 v222, v156, v157
	v_cvt_pk_bf16_f32 v223, v158, v159
	v_add_u32_e32 v253, 0xde801b54, v252
	v_cmp_gt_u32_e32 vcc, 0x3bff7543, v253
	s_cmp_lg_u64 vcc, exec
	s_cbranch_scc1 .Lfzsb1_c2
	v_add_f32_e32 v14, v14, v252
	s_branch .LBB0_2121

.LBB0_2171:
.LBB0_2173:
	v_mov_b32_e32 v252, v15
	v_mov_b32_e32 v253, v14
	s_nop 1
	v_permlane32_swap_b32_e32 v15, v252
	v_permlane32_swap_b32_e32 v14, v253
	v_add_f32_e32 v15, v15, v252
	v_add_f32_e32 v14, v14, v253
	v_mov_b32_e32 v2, v228
	s_nop 0
	v_bfe_u32 v5, v2, 5, 1
	v_and_b32_e32 v3, 0x3fffffc0, v2
	v_and_b32_e32 v0, 31, v2
	v_lshl_add_u32 v3, v3, 2, s18
	v_cmp_eq_u32_e32 vcc, 0, v5
	s_and_saveexec_b64 s[0:1], vcc
	s_cbranch_execz .LBB0_2094
	v_div_scale_f32 v4, s[4:5], v15, v15, 1.0
	v_rcp_f32_e32 v6, v4
	v_div_scale_f32 v7, vcc, 1.0, v15, 1.0
	v_fma_f32 v8, -v4, v6, 1.0
	v_fmac_f32_e32 v6, v8, v6
	v_mul_f32_e32 v8, v7, v6
	v_fma_f32 v9, -v4, v8, v7
	v_fmac_f32_e32 v8, v9, v6
	v_fma_f32 v4, -v4, v8, v7
	v_div_scale_f32 v7, s[4:5], v14, v14, v229
	v_rcp_f32_e32 v9, v7
	v_div_fmas_f32 v4, v4, v6, v8
	v_div_fixup_f32 v4, v4, v15, 1.0
	v_lshl_add_u32 v6, v0, 2, v3
	v_fma_f32 v8, -v7, v9, 1.0
	v_fmac_f32_e32 v9, v8, v9
	v_div_scale_f32 v8, vcc, v229, v14, v229
	v_mul_f32_e32 v10, v8, v9
	v_fma_f32 v11, -v7, v10, v8
	v_fmac_f32_e32 v10, v11, v9
	v_fma_f32 v7, -v7, v10, v8
	v_div_fmas_f32 v7, v7, v9, v10
	v_div_fixup_f32 v7, v7, v14, v229
	ds_write2_b32 v6, v4, v7 offset1:32
	s_branch .LBB0_2094
